# P0 prep loop: two rows prefetched ahead (two staging sets, loop body duplicated)
# baseline (speedup 1.0000x reference)
.LBB0_15:
	v_mov_b32_e32 v4, v214
	s_cmpk_lt_i32 s8, 0x4000
	s_barrier
	s_cbranch_scc0 .LBB0_20
	v_mbcnt_lo_u32_b32 v1, -1, 0
	v_mbcnt_hi_u32_b32 v2, -1, v1
	v_and_b32_e32 v1, 64, v2
	v_add_u32_e32 v3, 64, v1
	v_xor_b32_e32 v1, 1, v2
	v_cmp_lt_i32_e32 vcc, v1, v3
	v_xor_b32_e32 v6, 2, v2
	v_xor_b32_e32 v7, 4, v2
	v_cndmask_b32_e32 v1, v2, v1, vcc
	v_cmp_lt_i32_e32 vcc, v6, v3
	v_xor_b32_e32 v8, 8, v2
	v_xor_b32_e32 v9, 16, v2
	v_cndmask_b32_e32 v6, v2, v6, vcc
	v_cmp_lt_i32_e32 vcc, v7, v3
	s_ashr_i32 s9, s8, 31
	s_load_dwordx2 s[14:15], s[4:5], 0x0
	s_load_dwordx2 s[16:17], s[4:5], 0xd8
	v_cndmask_b32_e32 v7, v2, v7, vcc
	v_cmp_lt_i32_e32 vcc, v8, v3
	v_xor_b32_e32 v10, 32, v2
	s_lshl_b64 s[4:5], s[8:9], 4
	v_cndmask_b32_e32 v8, v2, v8, vcc
	v_cmp_lt_i32_e32 vcc, v9, v3
	s_add_u32 s12, s4, 0x10000
	v_ashrrev_i32_e32 v5, 31, v4
	v_cndmask_b32_e32 v9, v2, v9, vcc
	v_cmp_lt_i32_e32 vcc, v10, v3
	s_addc_u32 s13, s5, 0
	s_ashr_i32 s11, s10, 31
	v_cndmask_b32_e32 v2, v2, v10, vcc
	s_lshl_b64 s[4:5], s[8:9], 11
	v_lshlrev_b32_e32 v10, 2, v2
	s_lshl_b64 s[18:19], s[10:11], 4
	v_lshl_add_u64 v[2:3], v[4:5], 3, s[4:5]
	s_lshl_b64 s[20:21], s[10:11], 11
	s_lshl_b64 s[4:5], s[8:9], 12
	s_waitcnt lgkmcnt(0)
	s_add_u32 s4, s14, s4
	s_addc_u32 s5, s15, s5
	v_cmp_eq_u32_e32 vcc, 0, v4
	v_lshl_add_u64 v[4:5], v[4:5], 4, s[4:5]
	s_mov_b64 s[4:5], 0xc00
	v_lshlrev_b32_e32 v1, 2, v1
	v_lshlrev_b32_e32 v6, 2, v6
	v_lshlrev_b32_e32 v7, 2, v7
	v_lshlrev_b32_e32 v8, 2, v8
	v_lshlrev_b32_e32 v9, 2, v9
	v_lshl_add_u64 v[4:5], v[4:5], 0, s[4:5]
	s_lshl_b64 s[22:23], s[10:11], 12
	s_movk_i32 s9, 0x7fff
	s_mov_b32 s11, 0xffff0000
	s_mov_b32 s14, 0x3200000
	v_mov_b32_e32 v11, 0
	global_load_dwordx4 v[60:63], v[4:5], off offset:-3072
	global_load_dwordx4 v[64:67], v[4:5], off offset:-2048
	global_load_dwordx4 v[68:71], v[4:5], off offset:-1024
	global_load_dwordx4 v[72:75], v[4:5], off
	s_lshl_b64 s[76:77], s[22:23], 1
	s_add_i32 s74, s8, s10
	s_cmpk_gt_i32 s74, 0x3fff
	s_cbranch_scc1 .Lprep_pro1
	v_lshl_add_u64 v[76:77], v[4:5], 0, s[22:23]
	global_load_dwordx4 v[114:117], v[76:77], off offset:-3072
	global_load_dwordx4 v[118:121], v[76:77], off offset:-2048
	global_load_dwordx4 v[122:125], v[76:77], off offset:-1024
	global_load_dwordx4 v[126:129], v[76:77], off
	s_waitcnt vmcnt(4)
	s_branch .Lprep_pro2

.Lprep_pro2:
	v_mov_b64_e32 v[12:13], v[60:61]
	v_mov_b64_e32 v[14:15], v[62:63]
	v_mov_b64_e32 v[16:17], v[64:65]
	v_mov_b64_e32 v[18:19], v[66:67]
	v_mov_b64_e32 v[20:21], v[68:69]
	v_mov_b64_e32 v[22:23], v[70:71]
	v_mov_b64_e32 v[24:25], v[72:73]
	v_mov_b64_e32 v[26:27], v[74:75]
.Lprep_a:
	s_waitcnt lgkmcnt(0)
	s_mov_b32 s75, 5
	s_lshl_b32 s74, s10, 1
	s_add_i32 s74, s74, s8
	s_cmpk_gt_i32 s74, 0x3fff
	s_cbranch_scc1 .Lprep_a_nopf
	v_lshl_add_u64 v[76:77], v[4:5], 0, s[76:77]
	global_load_dwordx4 v[60:63], v[76:77], off offset:-3072
	global_load_dwordx4 v[64:67], v[76:77], off offset:-2048
	global_load_dwordx4 v[68:71], v[76:77], off offset:-1024
	global_load_dwordx4 v[72:75], v[76:77], off
	s_mov_b32 s75, 9

.Lprep_a_17:
	s_or_b64 exec, exec, s[4:5]
	s_add_i32 s8, s8, s10
	s_add_u32 s12, s12, s18
	s_addc_u32 s13, s13, s19
	v_lshl_add_u64 v[2:3], v[2:3], 0, s[20:21]
	s_cmpk_gt_i32 s8, 0x3fff
	v_lshl_add_u64 v[4:5], v[4:5], 0, s[22:23]
	s_cbranch_scc1 .LBB0_20
	s_cmp_eq_u32 s75, 9
	s_cbranch_scc1 .Lprep_a_w9
	s_waitcnt vmcnt(5)
	s_branch .Lprep_a_cp
.Lprep_a_w9:
	s_waitcnt vmcnt(9)
.Lprep_a_cp:
	v_mov_b64_e32 v[12:13], v[114:115]
	v_mov_b64_e32 v[14:15], v[116:117]
	v_mov_b64_e32 v[16:17], v[118:119]
	v_mov_b64_e32 v[18:19], v[120:121]
	v_mov_b64_e32 v[20:21], v[122:123]
	v_mov_b64_e32 v[22:23], v[124:125]
	v_mov_b64_e32 v[24:25], v[126:127]
	v_mov_b64_e32 v[26:27], v[128:129]
.Lprep_b:
	s_waitcnt lgkmcnt(0)
	s_mov_b32 s75, 5
	s_lshl_b32 s74, s10, 1
	s_add_i32 s74, s74, s8
	s_cmpk_gt_i32 s74, 0x3fff
	s_cbranch_scc1 .Lprep_b_nopf
	v_lshl_add_u64 v[76:77], v[4:5], 0, s[76:77]
	global_load_dwordx4 v[114:117], v[76:77], off offset:-3072
	global_load_dwordx4 v[118:121], v[76:77], off offset:-2048
	global_load_dwordx4 v[122:125], v[76:77], off offset:-1024
	global_load_dwordx4 v[126:129], v[76:77], off
	s_mov_b32 s75, 9

.Lprep_b_cp:
	v_mov_b64_e32 v[12:13], v[60:61]
	v_mov_b64_e32 v[14:15], v[62:63]
	v_mov_b64_e32 v[16:17], v[64:65]
	v_mov_b64_e32 v[18:19], v[66:67]
	v_mov_b64_e32 v[20:21], v[68:69]
	v_mov_b64_e32 v[22:23], v[70:71]
	v_mov_b64_e32 v[24:25], v[72:73]
	v_mov_b64_e32 v[26:27], v[74:75]
	s_branch .Lprep_a
